# merge epilogue: one pass of dword loads warms all gate cache lines of the tile so the later gate batches hit L2
# baseline (speedup 1.0000x reference)
.LBB0_1319:
	s_add_i32 s65, s2, 2
	s_add_u32 s52, s50, 0x100
	s_addc_u32 s53, s51, 0
	s_add_i32 s87, 0, 0x10000
	v_add_u32_e32 v209, s87, v202
	ds_read_b128 v[130:133], v209
	ds_read_b128 v[134:137], v209 offset:1024
	ds_read_b128 v[138:141], v209 offset:2048
	ds_read_b128 v[142:145], v209 offset:3072
	s_cmp_eq_u32 s13, s2
	s_cselect_b32 s55, s57, s53
	s_cselect_b32 s54, s15, s52
	s_cselect_b32 s70, 0x200, s12
	s_cselect_b32 s2, vcc_lo, s58
	s_cselect_b32 s3, vcc_hi, s64
	s_add_u32 s22, s50, s18
	s_addc_u32 s23, s51, s19
	s_add_i32 s17, s60, 0xc000
	v_add_u32_e32 v158, v170, v128
	s_mov_b32 m0, s17
	s_add_i32 s86, s60, 0xe000
	ds_read_b128 v[146:149], v203
	ds_read_b128 v[150:153], v203 offset:1024
	ds_read_b128 v[154:157], v203 offset:2048
	ds_read_b128 v[174:177], v203 offset:3072
	ds_read_b128 v[178:181], v203 offset:4096
	ds_read_b128 v[182:185], v203 offset:5120
	ds_read_b128 v[212:215], v203 offset:6144
	ds_read_b128 v[216:219], v203 offset:7168
	global_load_lds_dwordx4 v158, s[22:23]
	v_add_u32_e32 v158, v172, v129
	s_mov_b32 m0, s86
	s_nop 0
	global_load_lds_dwordx4 v158, s[22:23]
	s_waitcnt lgkmcnt(8)
	s_barrier
	s_waitcnt lgkmcnt(0)
	s_setprio 1
	s_waitcnt lgkmcnt(0)
	v_mfma_f32_16x16x32_bf16 v[124:127], v[130:133], v[146:149], v[124:127]
	v_mfma_f32_16x16x32_bf16 v[120:123], v[138:141], v[146:149], v[120:123]
	v_mfma_f32_16x16x32_bf16 v[116:119], v[130:133], v[154:157], v[116:119]
	v_mfma_f32_16x16x32_bf16 v[112:115], v[138:141], v[154:157], v[112:115]
	v_mfma_f32_16x16x32_bf16 v[108:111], v[130:133], v[178:181], v[108:111]
	v_mfma_f32_16x16x32_bf16 v[104:107], v[138:141], v[178:181], v[104:107]
	v_mfma_f32_16x16x32_bf16 v[96:99], v[130:133], v[212:215], v[96:99]
	v_mfma_f32_16x16x32_bf16 v[92:95], v[138:141], v[212:215], v[92:95]
	v_mfma_f32_16x16x32_bf16 v[124:127], v[134:137], v[150:153], v[124:127]
	v_mfma_f32_16x16x32_bf16 v[120:123], v[142:145], v[150:153], v[120:123]
	v_mfma_f32_16x16x32_bf16 v[116:119], v[134:137], v[174:177], v[116:119]
	v_mfma_f32_16x16x32_bf16 v[112:115], v[142:145], v[174:177], v[112:115]
	v_mfma_f32_16x16x32_bf16 v[108:111], v[134:137], v[182:185], v[108:111]
	v_mfma_f32_16x16x32_bf16 v[104:107], v[142:145], v[182:185], v[104:107]
	v_mfma_f32_16x16x32_bf16 v[96:99], v[134:137], v[216:219], v[96:99]
	v_mfma_f32_16x16x32_bf16 v[92:95], v[142:145], v[216:219], v[92:95]
	s_setprio 0
	s_barrier
	s_add_i32 s37, 0, 0x14000
	s_add_i32 s87, s87, s59
	v_add_u32_e32 v210, s37, v202
	v_mad_u64_u32 v[158:159], s[22:23], s70, v199, v[170:171]
	s_mov_b32 m0, s87
	s_add_i32 s36, s87, 0x2000
	ds_read_b128 v[220:223], v210
	ds_read_b128 v[224:227], v210 offset:1024
	ds_read_b128 v[228:231], v210 offset:2048
	ds_read_b128 v[232:235], v210 offset:3072
	global_load_lds_dwordx4 v158, s[2:3]
	v_mad_u64_u32 v[236:237], s[22:23], s70, v200, v[172:173]
	s_mov_b32 m0, s36
	v_mov_b32_e32 v159, v161
	global_load_lds_dwordx4 v236, s[2:3]
	s_barrier
	s_waitcnt lgkmcnt(0)
	v_mov_b32_e32 v237, v161
	v_lshl_add_u64 v[238:239], s[2:3], 0, v[158:159]
	v_lshl_add_u64 v[240:241], s[2:3], 0, v[236:237]
	s_setprio 1
	s_waitcnt lgkmcnt(0)
	v_mfma_f32_16x16x32_bf16 v[44:47], v[220:223], v[146:149], v[44:47]
	v_mfma_f32_16x16x32_bf16 v[40:43], v[228:231], v[146:149], v[40:43]
	v_mfma_f32_16x16x32_bf16 v[36:39], v[220:223], v[154:157], v[36:39]
	v_mfma_f32_16x16x32_bf16 v[32:35], v[228:231], v[154:157], v[32:35]
	v_mfma_f32_16x16x32_bf16 v[100:103], v[220:223], v[178:181], v[100:103]
	v_mfma_f32_16x16x32_bf16 v[88:91], v[228:231], v[178:181], v[88:91]
	v_mfma_f32_16x16x32_bf16 v[84:87], v[220:223], v[212:215], v[84:87]
	v_mfma_f32_16x16x32_bf16 v[80:83], v[228:231], v[212:215], v[80:83]
	v_mfma_f32_16x16x32_bf16 v[44:47], v[224:227], v[150:153], v[44:47]
	v_mfma_f32_16x16x32_bf16 v[40:43], v[232:235], v[150:153], v[40:43]
	v_mfma_f32_16x16x32_bf16 v[36:39], v[224:227], v[174:177], v[36:39]
	v_mfma_f32_16x16x32_bf16 v[32:35], v[232:235], v[174:177], v[32:35]
	v_mfma_f32_16x16x32_bf16 v[100:103], v[224:227], v[182:185], v[100:103]
	v_mfma_f32_16x16x32_bf16 v[88:91], v[232:235], v[182:185], v[88:91]
	v_mfma_f32_16x16x32_bf16 v[84:87], v[224:227], v[216:219], v[84:87]
	v_mfma_f32_16x16x32_bf16 v[80:83], v[232:235], v[216:219], v[80:83]
	s_setprio 0
	s_mov_b32 m0, s60
	v_mad_u64_u32 v[242:243], s[22:23], s70, v171, v[170:171]
	s_barrier
	ds_read_b128 v[146:149], v203 offset:16384
	ds_read_b128 v[150:153], v203 offset:17408
	ds_read_b128 v[154:157], v203 offset:18432
	ds_read_b128 v[174:177], v203 offset:19456
	ds_read_b128 v[178:181], v203 offset:20480
	ds_read_b128 v[182:185], v203 offset:21504
	ds_read_b128 v[212:215], v203 offset:22528
	ds_read_b128 v[216:219], v203 offset:23552
	global_load_lds_dwordx4 v242, s[54:55]
	v_mad_u64_u32 v[244:245], s[22:23], s70, v173, v[172:173]
	s_mov_b32 m0, s61
	v_mov_b32_e32 v243, v161
	global_load_lds_dwordx4 v244, s[54:55]
	s_barrier
	s_waitcnt lgkmcnt(0)
	v_mov_b32_e32 v245, v161
	v_lshl_add_u64 v[246:247], s[54:55], 0, v[242:243]
	v_lshl_add_u64 v[248:249], s[54:55], 0, v[244:245]
	s_setprio 1
	s_waitcnt lgkmcnt(0)
	v_mfma_f32_16x16x32_bf16 v[76:79], v[130:133], v[146:149], v[76:79]
	s_lshl_b64 s[22:23], s[70:71], 8
	v_mfma_f32_16x16x32_bf16 v[72:75], v[138:141], v[146:149], v[72:75]
	v_mfma_f32_16x16x32_bf16 v[64:67], v[130:133], v[154:157], v[64:67]
	v_mfma_f32_16x16x32_bf16 v[60:63], v[138:141], v[154:157], v[60:63]
	v_mfma_f32_16x16x32_bf16 v[28:31], v[130:133], v[178:181], v[28:31]
	v_mfma_f32_16x16x32_bf16 v[24:27], v[138:141], v[178:181], v[24:27]
	v_mfma_f32_16x16x32_bf16 v[12:15], v[130:133], v[212:215], v[12:15]
	v_mfma_f32_16x16x32_bf16 v[8:11], v[138:141], v[212:215], v[8:11]
	v_mfma_f32_16x16x32_bf16 v[76:79], v[134:137], v[150:153], v[76:79]
	v_mfma_f32_16x16x32_bf16 v[72:75], v[142:145], v[150:153], v[72:75]
	v_mfma_f32_16x16x32_bf16 v[64:67], v[134:137], v[174:177], v[64:67]
	v_mfma_f32_16x16x32_bf16 v[60:63], v[142:145], v[174:177], v[60:63]
	v_mfma_f32_16x16x32_bf16 v[28:31], v[134:137], v[182:185], v[28:31]
	v_mfma_f32_16x16x32_bf16 v[24:27], v[142:145], v[182:185], v[24:27]
	v_mfma_f32_16x16x32_bf16 v[12:15], v[134:137], v[216:219], v[12:15]
	v_mfma_f32_16x16x32_bf16 v[8:11], v[142:145], v[216:219], v[8:11]
	s_setprio 0
	s_barrier
	s_add_u32 s2, s2, s22
	s_addc_u32 s3, s3, s23
	s_add_i32 s37, s37, s59
	s_mov_b32 m0, s37
	s_add_i32 s70, s37, 0x2000
	global_load_lds_dwordx4 v158, s[2:3]
	s_mov_b32 m0, s70
	v_lshl_add_u64 v[158:159], s[2:3], 0, v[158:159]
	global_load_lds_dwordx4 v236, s[2:3]
	s_waitcnt vmcnt(6)
	v_lshl_add_u64 v[250:251], s[2:3], 0, v[236:237]
	s_barrier
	s_setprio 1
	v_mfma_f32_16x16x32_bf16 v[68:71], v[220:223], v[146:149], v[68:71]
	v_mfma_f32_16x16x32_bf16 v[56:59], v[228:231], v[146:149], v[56:59]
	v_mfma_f32_16x16x32_bf16 v[52:55], v[220:223], v[154:157], v[52:55]
	v_mfma_f32_16x16x32_bf16 v[48:51], v[228:231], v[154:157], v[48:51]
	v_mfma_f32_16x16x32_bf16 v[20:23], v[220:223], v[178:181], v[20:23]
	v_mfma_f32_16x16x32_bf16 v[16:19], v[228:231], v[178:181], v[16:19]
	v_mfma_f32_16x16x32_bf16 v[4:7], v[220:223], v[212:215], v[4:7]
	v_mfma_f32_16x16x32_bf16 v[0:3], v[228:231], v[212:215], v[0:3]
	v_mfma_f32_16x16x32_bf16 v[68:71], v[224:227], v[150:153], v[68:71]
	v_mfma_f32_16x16x32_bf16 v[56:59], v[232:235], v[150:153], v[56:59]
	v_mfma_f32_16x16x32_bf16 v[52:55], v[224:227], v[174:177], v[52:55]
	v_mfma_f32_16x16x32_bf16 v[48:51], v[232:235], v[174:177], v[48:51]
	v_mfma_f32_16x16x32_bf16 v[20:23], v[224:227], v[182:185], v[20:23]
	v_mfma_f32_16x16x32_bf16 v[16:19], v[232:235], v[182:185], v[16:19]
	v_mfma_f32_16x16x32_bf16 v[4:7], v[224:227], v[216:219], v[4:7]
	v_mfma_f32_16x16x32_bf16 v[0:3], v[232:235], v[216:219], v[0:3]
	s_setprio 0
	s_add_i32 s50, 0, 0x18000
	v_add_u32_e32 v211, s50, v202
	s_barrier
	ds_read_b128 v[130:133], v211
	ds_read_b128 v[134:137], v211 offset:1024
	ds_read_b128 v[138:141], v211 offset:2048
	ds_read_b128 v[142:145], v211 offset:3072
	s_add_u32 s2, s54, s22
	s_addc_u32 s3, s55, s23
	s_mov_b32 m0, s62
	ds_read_b128 v[146:149], v203 offset:32768
	ds_read_b128 v[150:153], v203 offset:33792
	ds_read_b128 v[154:157], v203 offset:34816
	ds_read_b128 v[174:177], v203 offset:35840
	ds_read_b128 v[178:181], v203 offset:36864
	ds_read_b128 v[182:185], v203 offset:37888
	ds_read_b128 v[214:217], v203 offset:38912
	ds_read_b128 v[218:221], v203 offset:39936
	global_load_lds_dwordx4 v242, s[2:3]
	s_mov_b32 m0, s63
	s_nop 0
	global_load_lds_dwordx4 v244, s[2:3]
	s_waitcnt lgkmcnt(8)
	s_barrier
	s_waitcnt lgkmcnt(0)
	s_setprio 1
	s_waitcnt lgkmcnt(0)
	v_mfma_f32_16x16x32_bf16 v[124:127], v[130:133], v[146:149], v[124:127]
	v_mfma_f32_16x16x32_bf16 v[120:123], v[138:141], v[146:149], v[120:123]
	v_mfma_f32_16x16x32_bf16 v[116:119], v[130:133], v[154:157], v[116:119]
	v_mfma_f32_16x16x32_bf16 v[112:115], v[138:141], v[154:157], v[112:115]
	v_mfma_f32_16x16x32_bf16 v[108:111], v[130:133], v[178:181], v[108:111]
	v_mfma_f32_16x16x32_bf16 v[104:107], v[138:141], v[178:181], v[104:107]
	v_mfma_f32_16x16x32_bf16 v[96:99], v[130:133], v[214:217], v[96:99]
	v_mfma_f32_16x16x32_bf16 v[92:95], v[138:141], v[214:217], v[92:95]
	v_mfma_f32_16x16x32_bf16 v[124:127], v[134:137], v[150:153], v[124:127]
	v_mfma_f32_16x16x32_bf16 v[120:123], v[142:145], v[150:153], v[120:123]
	v_mfma_f32_16x16x32_bf16 v[116:119], v[134:137], v[174:177], v[116:119]
	v_mfma_f32_16x16x32_bf16 v[112:115], v[142:145], v[174:177], v[112:115]
	v_mfma_f32_16x16x32_bf16 v[108:111], v[134:137], v[182:185], v[108:111]
	v_mfma_f32_16x16x32_bf16 v[104:107], v[142:145], v[182:185], v[104:107]
	v_mfma_f32_16x16x32_bf16 v[96:99], v[134:137], v[218:221], v[96:99]
	v_mfma_f32_16x16x32_bf16 v[92:95], v[142:145], v[218:221], v[92:95]
	s_setprio 0
	s_barrier
	s_add_i32 s22, 0, 0x1c000
	s_add_i32 s54, s50, s59
	v_add_u32_e32 v212, s22, v202
	v_lshl_add_u64 v[238:239], v[238:239], 0, s[78:79]
	s_mov_b32 m0, s54
	s_add_i32 s55, s54, 0x2000
	ds_read_b128 v[222:225], v212
	ds_read_b128 v[226:229], v212 offset:1024
	ds_read_b128 v[230:233], v212 offset:2048
	ds_read_b128 v[234:237], v212 offset:3072
	global_load_lds_dwordx4 v[238:239], off
	v_lshl_add_u64 v[238:239], v[240:241], 0, s[78:79]
	s_mov_b32 m0, s55
	s_nop 0
	global_load_lds_dwordx4 v[238:239], off
	s_barrier
	s_waitcnt lgkmcnt(0)
	s_setprio 1
	s_waitcnt lgkmcnt(0)
	v_mfma_f32_16x16x32_bf16 v[44:47], v[222:225], v[146:149], v[44:47]
	v_mfma_f32_16x16x32_bf16 v[40:43], v[230:233], v[146:149], v[40:43]
	v_mfma_f32_16x16x32_bf16 v[36:39], v[222:225], v[154:157], v[36:39]
	v_mfma_f32_16x16x32_bf16 v[32:35], v[230:233], v[154:157], v[32:35]
	v_mfma_f32_16x16x32_bf16 v[100:103], v[222:225], v[178:181], v[100:103]
	v_mfma_f32_16x16x32_bf16 v[88:91], v[230:233], v[178:181], v[88:91]
	v_mfma_f32_16x16x32_bf16 v[84:87], v[222:225], v[214:217], v[84:87]
	v_mfma_f32_16x16x32_bf16 v[80:83], v[230:233], v[214:217], v[80:83]
	v_mfma_f32_16x16x32_bf16 v[44:47], v[226:229], v[150:153], v[44:47]
	v_mfma_f32_16x16x32_bf16 v[40:43], v[234:237], v[150:153], v[40:43]
	v_mfma_f32_16x16x32_bf16 v[36:39], v[226:229], v[174:177], v[36:39]
	v_mfma_f32_16x16x32_bf16 v[32:35], v[234:237], v[174:177], v[32:35]
	v_mfma_f32_16x16x32_bf16 v[100:103], v[226:229], v[182:185], v[100:103]
	v_mfma_f32_16x16x32_bf16 v[88:91], v[234:237], v[182:185], v[88:91]
	v_mfma_f32_16x16x32_bf16 v[84:87], v[226:229], v[218:221], v[84:87]
	v_mfma_f32_16x16x32_bf16 v[80:83], v[234:237], v[218:221], v[80:83]
	s_setprio 0
	s_mov_b32 m0, s74
	v_lshl_add_u64 v[238:239], v[246:247], 0, s[78:79]
	s_barrier
	ds_read_b128 v[146:149], v203 offset:49152
	ds_read_b128 v[150:153], v203 offset:50176
	ds_read_b128 v[154:157], v203 offset:51200
	ds_read_b128 v[174:177], v203 offset:52224
	ds_read_b128 v[178:181], v203 offset:53248
	ds_read_b128 v[182:185], v203 offset:54272
	ds_read_b128 v[214:217], v203 offset:55296
	ds_read_b128 v[218:221], v203 offset:56320
	global_load_lds_dwordx4 v[238:239], off
	v_lshl_add_u64 v[238:239], v[248:249], 0, s[78:79]
	s_mov_b32 m0, s75
	s_nop 0
	global_load_lds_dwordx4 v[238:239], off
	s_barrier
;     DI void mid(AccT& acc, const Unit& u, int seg, int wr, int wc, int fr, int fq) const {
;         const int row0 = u.pm * BM + wr * 64 + fr, col0 = u.pn * BM + wc * 32 + 8 * fq;
;         const unsigned char* pa = (const unsigned char*)G + (size_t)row0 * NGATE + seg * 2048 + col0;
; #pragma unroll
;         for (int ai = 0; ai < 2; ++ai) {
; #pragma unroll
;             for (int mh = 0; mh < 2; ++mh) {
;                 u32x2 ra[2][2], rb[2][2];
; #pragma unroll
;                 for (int mm = 0; mm < 2; ++mm)
; #pragma unroll
;                     for (int bj = 0; bj < 2; ++bj) { const unsigned char* p = pa + (size_t)(mm * 16) * NGATE + bj * HALF; ra[mm][bj] = *(const u32x2*)p; rb[mm][bj] = *(const u32x2*)(p + 2048); }
	s_waitcnt lgkmcnt(0)
	s_setprio 1
	s_waitcnt lgkmcnt(0)
	v_mfma_f32_16x16x32_bf16 v[76:79], v[130:133], v[146:149], v[76:79]
	v_mfma_f32_16x16x32_bf16 v[72:75], v[138:141], v[146:149], v[72:75]
	v_mfma_f32_16x16x32_bf16 v[64:67], v[130:133], v[154:157], v[64:67]
	v_mfma_f32_16x16x32_bf16 v[60:63], v[138:141], v[154:157], v[60:63]
	v_mfma_f32_16x16x32_bf16 v[28:31], v[130:133], v[178:181], v[28:31]
	v_mfma_f32_16x16x32_bf16 v[24:27], v[138:141], v[178:181], v[24:27]
	v_mfma_f32_16x16x32_bf16 v[12:15], v[130:133], v[214:217], v[12:15]
	v_mfma_f32_16x16x32_bf16 v[8:11], v[138:141], v[214:217], v[8:11]
	v_mfma_f32_16x16x32_bf16 v[76:79], v[134:137], v[150:153], v[76:79]
	v_mfma_f32_16x16x32_bf16 v[72:75], v[142:145], v[150:153], v[72:75]
	v_mfma_f32_16x16x32_bf16 v[64:67], v[134:137], v[174:177], v[64:67]
	v_mfma_f32_16x16x32_bf16 v[60:63], v[142:145], v[174:177], v[60:63]
	v_mfma_f32_16x16x32_bf16 v[28:31], v[134:137], v[182:185], v[28:31]
	v_mfma_f32_16x16x32_bf16 v[24:27], v[142:145], v[182:185], v[24:27]
	v_mfma_f32_16x16x32_bf16 v[12:15], v[134:137], v[218:221], v[12:15]
	v_mfma_f32_16x16x32_bf16 v[8:11], v[142:145], v[218:221], v[8:11]
	s_setprio 0
	s_barrier
	s_add_i32 s22, s22, s59
	v_lshl_add_u64 v[130:131], v[158:159], 0, s[78:79]
	s_mov_b32 m0, s22
	s_add_i32 s23, s22, 0x2000
	global_load_lds_dwordx4 v[130:131], off
	v_lshl_add_u64 v[130:131], v[250:251], 0, s[78:79]
	s_mov_b32 m0, s23
	s_nop 0
	global_load_lds_dwordx4 v[130:131], off
	s_waitcnt vmcnt(6)
	s_barrier
	s_setprio 1
	v_mfma_f32_16x16x32_bf16 v[68:71], v[222:225], v[146:149], v[68:71]
	v_mfma_f32_16x16x32_bf16 v[56:59], v[230:233], v[146:149], v[56:59]
	v_mfma_f32_16x16x32_bf16 v[52:55], v[222:225], v[154:157], v[52:55]
	v_mfma_f32_16x16x32_bf16 v[48:51], v[230:233], v[154:157], v[48:51]
	v_mfma_f32_16x16x32_bf16 v[20:23], v[222:225], v[178:181], v[20:23]
	v_mfma_f32_16x16x32_bf16 v[16:19], v[230:233], v[178:181], v[16:19]
	v_mfma_f32_16x16x32_bf16 v[4:7], v[222:225], v[214:217], v[4:7]
	v_mfma_f32_16x16x32_bf16 v[0:3], v[230:233], v[214:217], v[0:3]
	v_mfma_f32_16x16x32_bf16 v[68:71], v[226:229], v[150:153], v[68:71]
	v_mfma_f32_16x16x32_bf16 v[56:59], v[234:237], v[150:153], v[56:59]
	v_mfma_f32_16x16x32_bf16 v[52:55], v[226:229], v[174:177], v[52:55]
	v_mfma_f32_16x16x32_bf16 v[48:51], v[234:237], v[174:177], v[48:51]
	v_mfma_f32_16x16x32_bf16 v[20:23], v[226:229], v[182:185], v[20:23]
	v_mfma_f32_16x16x32_bf16 v[16:19], v[234:237], v[182:185], v[16:19]
	v_mfma_f32_16x16x32_bf16 v[4:7], v[226:229], v[218:221], v[4:7]
	v_mfma_f32_16x16x32_bf16 v[0:3], v[234:237], v[218:221], v[0:3]
	s_setprio 0
	s_add_u32 s58, s58, 0x100
	s_addc_u32 s64, s64, 0
	s_cmp_ge_u32 s65, s5
	s_mov_b64 s[50:51], s[52:53]
	s_mov_b32 s2, s65
	s_barrier
	s_cbranch_scc0 .LBB0_1319
	v_lshl_add_u32 v178, s14, 8, v201
	v_lshl_or_b32 v176, s16, 8, v208
	v_mov_b64_e32 v[128:129], s[44:45]
	s_movk_i32 s2, 0x1800
	v_mad_i64_i32 v[128:129], s[2:3], v178, s2, v[128:129]
	v_ashrrev_i32_e32 v177, 31, v176
	v_lshl_add_u64 v[174:175], v[128:129], 0, v[176:177]
	v_add_co_u32_e32 v216, vcc, 0x1000, v174
	s_nop 1
	v_addc_co_u32_e32 v217, vcc, 0, v175, vcc
	global_load_dword v213, v[216:217], off
	global_load_dword v213, v[216:217], off offset:128
	v_add_co_u32_e32 v214, vcc, 0x18000, v174
	s_nop 1
	v_addc_co_u32_e32 v215, vcc, 0, v175, vcc
	v_add_co_u32_e32 v216, vcc, 0x1000, v214
	s_nop 1
	v_addc_co_u32_e32 v217, vcc, 0, v215, vcc
	global_load_dword v213, v[216:217], off
	global_load_dword v213, v[216:217], off offset:128
	v_add_co_u32_e32 v214, vcc, 0x30000, v174
	s_nop 1
	v_addc_co_u32_e32 v215, vcc, 0, v175, vcc
	global_load_dword v213, v[214:215], off
	global_load_dword v213, v[214:215], off offset:128
	global_load_dword v213, v[214:215], off offset:2048
	global_load_dword v213, v[214:215], off offset:2176
	v_add_co_u32_e32 v216, vcc, 0x1000, v214
	s_nop 1
	v_addc_co_u32_e32 v217, vcc, 0, v215, vcc
	global_load_dword v213, v[216:217], off
	global_load_dword v213, v[216:217], off offset:128
	v_add_co_u32_e32 v214, vcc, 0x48000, v174
	s_nop 1
	v_addc_co_u32_e32 v215, vcc, 0, v175, vcc
	global_load_dword v213, v[214:215], off
	global_load_dword v213, v[214:215], off offset:128
	global_load_dword v213, v[214:215], off offset:2048
	global_load_dword v213, v[214:215], off offset:2176
	v_add_co_u32_e32 v216, vcc, 0x1000, v214
	s_nop 1
	v_addc_co_u32_e32 v217, vcc, 0, v215, vcc
	global_load_dword v213, v[216:217], off
	global_load_dword v213, v[216:217], off offset:128
	v_add_co_u32_e32 v214, vcc, 0xc0000, v174
	s_nop 1
	v_addc_co_u32_e32 v215, vcc, 0, v175, vcc
	global_load_dword v213, v[214:215], off
	global_load_dword v213, v[214:215], off offset:128
	global_load_dword v213, v[214:215], off offset:2048
	global_load_dword v213, v[214:215], off offset:2176
	v_add_co_u32_e32 v216, vcc, 0x1000, v214
	s_nop 1
	v_addc_co_u32_e32 v217, vcc, 0, v215, vcc
	global_load_dword v213, v[216:217], off
	global_load_dword v213, v[216:217], off offset:128
	v_add_co_u32_e32 v214, vcc, 0xd8000, v174
	s_nop 1
	v_addc_co_u32_e32 v215, vcc, 0, v175, vcc
	global_load_dword v213, v[214:215], off
	global_load_dword v213, v[214:215], off offset:128
	global_load_dword v213, v[214:215], off offset:2048
	global_load_dword v213, v[214:215], off offset:2176
	v_add_co_u32_e32 v216, vcc, 0x1000, v214
	s_nop 1
	v_addc_co_u32_e32 v217, vcc, 0, v215, vcc
	global_load_dword v213, v[216:217], off
	global_load_dword v213, v[216:217], off offset:128
	v_add_co_u32_e32 v214, vcc, 0xf0000, v174
	s_nop 1
	v_addc_co_u32_e32 v215, vcc, 0, v175, vcc
	global_load_dword v213, v[214:215], off
	global_load_dword v213, v[214:215], off offset:128
;     DI void mid(AccT& acc, const Unit& u, int seg, int wr, int wc, int fr, int fq) const {
;         const int row0 = u.pm * BM + wr * 64 + fr, col0 = u.pn * BM + wc * 32 + 8 * fq;
;         const unsigned char* pa = (const unsigned char*)G + (size_t)row0 * NGATE + seg * 2048 + col0;
; #pragma unroll
;         for (int ai = 0; ai < 2; ++ai) {
; #pragma unroll
;             for (int mh = 0; mh < 2; ++mh) {
;                 u32x2 ra[2][2], rb[2][2];
; #pragma unroll
;                 for (int mm = 0; mm < 2; ++mm)
; #pragma unroll
;                     for (int bj = 0; bj < 2; ++bj) { const unsigned char* p = pa + (size_t)(mm * 16) * NGATE + bj * HALF; ra[mm][bj] = *(const u32x2*)p; rb[mm][bj] = *(const u32x2*)(p + 2048); }
; #pragma unroll
;                 for (int mm = 0; mm < 2; ++mm)
; #pragma unroll
;                     for (int bj = 0; bj < 2; ++bj) {
;                         float ga[8], gb[8];
;                         unpack_gate8(ra[mm][bj], ga); unpack_gate8(rb[mm][bj], gb);
;                         const int m = 2 * mh + mm;
; #pragma unroll
;                         for (int j = 0; j < 4; ++j) { const float r0 = ga[j] * __builtin_amdgcn_rcpf(gb[j]), r1 = ga[4 + j] * __builtin_amdgcn_rcpf(gb[4 + j]);
;                             acc[ai][bj][m][0][j] *= r0; acc[ai][bj][m][1][j] *= r1; } }
	global_load_dword v213, v[214:215], off offset:2048
	global_load_dword v213, v[214:215], off offset:2176
	v_add_co_u32_e32 v216, vcc, 0x1000, v214
	s_nop 1
	v_addc_co_u32_e32 v217, vcc, 0, v215, vcc
	global_load_dword v213, v[216:217], off
	global_load_dword v213, v[216:217], off offset:128
	v_add_co_u32_e32 v214, vcc, 0x108000, v174
	s_nop 1
	v_addc_co_u32_e32 v215, vcc, 0, v175, vcc
	global_load_dword v213, v[214:215], off
	global_load_dword v213, v[214:215], off offset:128
	global_load_dword v213, v[214:215], off offset:2048
	global_load_dword v213, v[214:215], off offset:2176
	v_add_co_u32_e32 v216, vcc, 0x1000, v214
	s_nop 1
	v_addc_co_u32_e32 v217, vcc, 0, v215, vcc
	global_load_dword v213, v[216:217], off
	global_load_dword v213, v[216:217], off offset:128
	flat_load_dwordx2 v[128:129], v[174:175]
	flat_load_dwordx2 v[130:131], v[174:175] offset:2048
	flat_load_dwordx2 v[132:133], v[174:175] offset:128
	flat_load_dwordx2 v[134:135], v[174:175] offset:2176
	v_add_co_u32_e32 v136, vcc, 0x18000, v174
	v_lshl_add_u64 v[182:183], v[174:175], 0, s[24:25]
	s_nop 0
	v_addc_co_u32_e32 v137, vcc, 0, v175, vcc
	flat_load_dwordx2 v[144:145], v[136:137]
	flat_load_dwordx2 v[146:147], v[136:137] offset:2048
	flat_load_dwordx2 v[148:149], v[136:137] offset:128
	flat_load_dwordx2 v[150:151], v[136:137] offset:2176
	s_mov_b64 s[2:3], 0x800
	v_lshl_add_u64 v[180:181], v[174:175], 0, s[2:3]
	s_add_u32 s2, s29, s48
	s_addc_u32 s3, s76, s49
	s_add_u32 s16, s30, s10
	v_ashrrev_i32_e32 v179, 31, v178
	s_addc_u32 s18, s31, s11
	s_mov_b32 s5, -2
	s_mov_b64 s[10:11], 0
	s_waitcnt vmcnt(0) lgkmcnt(0)
	v_cvt_f32_ubyte2_e32 v138, v130
	v_cvt_f32_ubyte3_e32 v139, v130
	v_cvt_f32_ubyte0_e32 v136, v130
	v_cvt_f32_ubyte1_e32 v137, v130
	v_rcp_iflag_f32_e32 v138, v138
	v_rcp_iflag_f32_e32 v139, v139
	v_cvt_f32_ubyte0_e32 v140, v131
	v_cvt_f32_ubyte1_e32 v141, v131
	v_cvt_f32_ubyte2_e32 v142, v131
	v_cvt_f32_ubyte3_e32 v143, v131
	v_rcp_iflag_f32_e32 v130, v136
	v_rcp_iflag_f32_e32 v131, v137
	v_rcp_iflag_f32_e32 v136, v140
	v_rcp_iflag_f32_e32 v137, v141
	v_rcp_iflag_f32_e32 v152, v142
	v_rcp_iflag_f32_e32 v153, v143
	v_cvt_f32_ubyte3_e32 v141, v128
	v_cvt_f32_ubyte2_e32 v140, v128
	v_cvt_f32_ubyte1_e32 v143, v128
	v_cvt_f32_ubyte0_e32 v142, v128
	v_pk_mul_f32 v[138:139], v[138:139], v[140:141]
	v_pk_mul_f32 v[130:131], v[130:131], v[142:143]
	v_pk_mul_f32 v[142:143], v[126:127], v[138:139]
	v_cvt_f32_ubyte1_e32 v127, v129
	v_cvt_f32_ubyte0_e32 v126, v129
	v_pk_mul_f32 v[140:141], v[124:125], v[130:131]
	v_cvt_f32_ubyte3_e32 v125, v129
	v_cvt_f32_ubyte2_e32 v124, v129
	v_pk_mul_f32 v[126:127], v[136:137], v[126:127]
	v_pk_mul_f32 v[124:125], v[152:153], v[124:125]
	v_pk_mul_f32 v[136:137], v[120:121], v[126:127]
	v_cvt_f32_ubyte0_e32 v120, v134
	v_cvt_f32_ubyte1_e32 v121, v134
	v_pk_mul_f32 v[138:139], v[122:123], v[124:125]
	v_cvt_f32_ubyte2_e32 v124, v134
	v_cvt_f32_ubyte3_e32 v125, v134
	v_rcp_iflag_f32_e32 v120, v120
	v_rcp_iflag_f32_e32 v121, v121
	v_cvt_f32_ubyte2_e32 v126, v135
	v_cvt_f32_ubyte3_e32 v127, v135
	v_rcp_iflag_f32_e32 v124, v124
	v_rcp_iflag_f32_e32 v125, v125
	v_cvt_f32_ubyte0_e32 v122, v135
	v_cvt_f32_ubyte1_e32 v123, v135
	v_rcp_iflag_f32_e32 v126, v126
	v_rcp_iflag_f32_e32 v127, v127
	v_rcp_iflag_f32_e32 v122, v122
	v_rcp_iflag_f32_e32 v123, v123
	v_cvt_f32_ubyte1_e32 v131, v132
	v_cvt_f32_ubyte0_e32 v130, v132
	v_cvt_f32_ubyte3_e32 v129, v132
	v_cvt_f32_ubyte2_e32 v128, v132
	v_pk_mul_f32 v[120:121], v[120:121], v[130:131]
	v_pk_mul_f32 v[124:125], v[124:125], v[128:129]
	v_pk_mul_f32 v[44:45], v[44:45], v[120:121]
	v_cvt_f32_ubyte3_e32 v121, v133
	v_cvt_f32_ubyte2_e32 v120, v133
	v_pk_mul_f32 v[46:47], v[46:47], v[124:125]
	v_cvt_f32_ubyte1_e32 v125, v133
	v_cvt_f32_ubyte0_e32 v124, v133
	v_pk_mul_f32 v[120:121], v[126:127], v[120:121]
	v_pk_mul_f32 v[122:123], v[122:123], v[124:125]
	v_pk_mul_f32 v[42:43], v[42:43], v[120:121]
	v_cvt_f32_ubyte0_e32 v120, v146
	v_cvt_f32_ubyte1_e32 v121, v146
	v_cvt_f32_ubyte2_e32 v124, v146
	v_cvt_f32_ubyte3_e32 v125, v146
	v_rcp_iflag_f32_e32 v120, v120
	v_rcp_iflag_f32_e32 v121, v121
	v_rcp_iflag_f32_e32 v124, v124
	v_rcp_iflag_f32_e32 v125, v125
	v_pk_mul_f32 v[40:41], v[40:41], v[122:123]
	v_cvt_f32_ubyte0_e32 v122, v147
	v_cvt_f32_ubyte1_e32 v123, v147
	v_cvt_f32_ubyte2_e32 v126, v147
	v_cvt_f32_ubyte3_e32 v127, v147
	v_rcp_iflag_f32_e32 v122, v122
	v_rcp_iflag_f32_e32 v123, v123
	v_rcp_iflag_f32_e32 v126, v126
	v_rcp_iflag_f32_e32 v127, v127
	v_cvt_f32_ubyte3_e32 v129, v144
	v_cvt_f32_ubyte2_e32 v128, v144
	v_cvt_f32_ubyte1_e32 v131, v144
	v_cvt_f32_ubyte0_e32 v130, v144
	v_pk_mul_f32 v[120:121], v[120:121], v[130:131]
	v_pk_mul_f32 v[124:125], v[124:125], v[128:129]
	v_pk_mul_f32 v[132:133], v[116:117], v[120:121]
	v_pk_mul_f32 v[134:135], v[118:119], v[124:125]
	v_cvt_f32_ubyte3_e32 v117, v145
	v_cvt_f32_ubyte2_e32 v116, v145
	v_cvt_f32_ubyte1_e32 v119, v145
	v_cvt_f32_ubyte0_e32 v118, v145
	v_pk_mul_f32 v[118:119], v[122:123], v[118:119]
	v_pk_mul_f32 v[116:117], v[126:127], v[116:117]
	v_pk_mul_f32 v[128:129], v[112:113], v[118:119]
	v_pk_mul_f32 v[130:131], v[114:115], v[116:117]
	v_cvt_f32_ubyte0_e32 v112, v150
	v_cvt_f32_ubyte1_e32 v113, v150
	v_cvt_f32_ubyte2_e32 v116, v150
	v_cvt_f32_ubyte3_e32 v117, v150
	v_rcp_iflag_f32_e32 v112, v112
	v_rcp_iflag_f32_e32 v113, v113
	v_rcp_iflag_f32_e32 v116, v116
	v_rcp_iflag_f32_e32 v117, v117
	v_cvt_f32_ubyte0_e32 v114, v151
	v_cvt_f32_ubyte1_e32 v115, v151
	v_cvt_f32_ubyte2_e32 v118, v151
	v_cvt_f32_ubyte3_e32 v119, v151
	v_rcp_iflag_f32_e32 v114, v114
	v_rcp_iflag_f32_e32 v115, v115
	v_rcp_iflag_f32_e32 v118, v118
	v_rcp_iflag_f32_e32 v119, v119
	v_cvt_f32_ubyte3_e32 v121, v148
	v_cvt_f32_ubyte2_e32 v120, v148
	v_cvt_f32_ubyte1_e32 v123, v148
	v_cvt_f32_ubyte0_e32 v122, v148
	v_pk_mul_f32 v[112:113], v[112:113], v[122:123]
	v_pk_mul_f32 v[116:117], v[116:117], v[120:121]
	v_pk_mul_f32 v[36:37], v[36:37], v[112:113]
	v_pk_mul_f32 v[38:39], v[38:39], v[116:117]
	v_cvt_f32_ubyte3_e32 v113, v149
	v_cvt_f32_ubyte2_e32 v112, v149
	v_cvt_f32_ubyte1_e32 v117, v149
	v_cvt_f32_ubyte0_e32 v116, v149
	v_pk_mul_f32 v[114:115], v[114:115], v[116:117]
	v_pk_mul_f32 v[112:113], v[118:119], v[112:113]
	v_pk_mul_f32 v[32:33], v[32:33], v[114:115]
	v_pk_mul_f32 v[34:35], v[34:35], v[112:113]
	flat_load_dwordx2 v[114:115], v[182:183]
	flat_load_dwordx2 v[116:117], v[182:183] offset:2048
	flat_load_dwordx2 v[112:113], v[182:183] offset:128
	flat_load_dwordx2 v[118:119], v[182:183] offset:2176
	v_add_co_u32_e32 v120, vcc, s21, v182
	s_waitcnt vmcnt(0) lgkmcnt(0)
;     DI void mid(AccT& acc, const Unit& u, int seg, int wr, int wc, int fr, int fq) const {
;     ...
; #pragma unroll
;         for (int ai = 0; ai < 2; ++ai) {
; #pragma unroll
;             for (int mh = 0; mh < 2; ++mh) {
;                 u32x2 ra[2][2], rb[2][2];
; #pragma unroll
;                 for (int mm = 0; mm < 2; ++mm)
; #pragma unroll
;                     for (int bj = 0; bj < 2; ++bj) { const unsigned char* p = pa + (size_t)(mm * 16) * NGATE + bj * HALF; ra[mm][bj] = *(const u32x2*)p; rb[mm][bj] = *(const u32x2*)(p + 2048); }
; #pragma unroll
;                 for (int mm = 0; mm < 2; ++mm)
; #pragma unroll
;                     for (int bj = 0; bj < 2; ++bj) {
;                         float ga[8], gb[8];
;                         unpack_gate8(ra[mm][bj], ga); unpack_gate8(rb[mm][bj], gb);
;                         const int m = 2 * mh + mm;
; #pragma unroll
;                         for (int j = 0; j < 4; ++j) { const float r0 = ga[j] * __builtin_amdgcn_rcpf(gb[j]), r1 = ga[4 + j] * __builtin_amdgcn_rcpf(gb[4 + j]);
;                             acc[ai][bj][m][0][j] *= r0; acc[ai][bj][m][1][j] *= r1; } }
;                 pa += (size_t)(mh == 1 ? 96 : 32) * NGATE;
;                 asm volatile("" : "+v"(pa));
	v_cvt_f32_ubyte1_e32 v149, v114
	v_addc_co_u32_e32 v121, vcc, 0, v183, vcc
	flat_load_dwordx2 v[144:145], v[120:121]
	flat_load_dwordx2 v[146:147], v[120:121] offset:2048
	flat_load_dwordx2 v[184:185], v[120:121] offset:128
	flat_load_dwordx2 v[214:215], v[120:121] offset:2176
	v_cvt_f32_ubyte0_e32 v120, v116
	v_cvt_f32_ubyte1_e32 v121, v116
	v_cvt_f32_ubyte2_e32 v122, v116
	v_cvt_f32_ubyte3_e32 v123, v116
	v_cvt_f32_ubyte0_e32 v124, v117
	v_cvt_f32_ubyte1_e32 v125, v117
	v_cvt_f32_ubyte2_e32 v126, v117
	v_cvt_f32_ubyte3_e32 v127, v117
	v_rcp_iflag_f32_e32 v116, v120
	v_rcp_iflag_f32_e32 v117, v121
	v_rcp_iflag_f32_e32 v120, v124
	v_rcp_iflag_f32_e32 v121, v125
	v_rcp_iflag_f32_e32 v122, v122
	v_rcp_iflag_f32_e32 v124, v126
	v_rcp_iflag_f32_e32 v123, v123
	v_rcp_iflag_f32_e32 v125, v127
	v_cvt_f32_ubyte0_e32 v148, v114
	v_pk_mul_f32 v[116:117], v[116:117], v[148:149]
	v_cvt_f32_ubyte3_e32 v127, v114
	v_cvt_f32_ubyte2_e32 v126, v114
	v_pk_mul_f32 v[156:157], v[108:109], v[116:117]
	v_cvt_f32_ubyte3_e32 v109, v115
	v_cvt_f32_ubyte2_e32 v108, v115
	v_pk_mul_f32 v[122:123], v[122:123], v[126:127]
	v_pk_mul_f32 v[108:109], v[124:125], v[108:109]
	v_pk_mul_f32 v[158:159], v[110:111], v[122:123]
	v_cvt_f32_ubyte1_e32 v111, v115
	v_cvt_f32_ubyte0_e32 v110, v115
	v_pk_mul_f32 v[154:155], v[106:107], v[108:109]
	v_cvt_f32_ubyte2_e32 v108, v118
	v_cvt_f32_ubyte3_e32 v109, v118
	v_pk_mul_f32 v[110:111], v[120:121], v[110:111]
	v_rcp_iflag_f32_e32 v108, v108
	v_rcp_iflag_f32_e32 v109, v109
	v_pk_mul_f32 v[152:153], v[104:105], v[110:111]
	v_cvt_f32_ubyte0_e32 v104, v118
	v_cvt_f32_ubyte1_e32 v105, v118
	v_cvt_f32_ubyte0_e32 v106, v119
	v_cvt_f32_ubyte1_e32 v107, v119
	v_rcp_iflag_f32_e32 v104, v104
	v_rcp_iflag_f32_e32 v106, v106
	v_rcp_iflag_f32_e32 v105, v105
	v_rcp_iflag_f32_e32 v107, v107
	v_cvt_f32_ubyte2_e32 v110, v119
	v_cvt_f32_ubyte3_e32 v111, v119
	v_cvt_f32_ubyte3_e32 v115, v112
	v_cvt_f32_ubyte2_e32 v114, v112
	v_rcp_iflag_f32_e32 v110, v110
	v_rcp_iflag_f32_e32 v111, v111
	v_pk_mul_f32 v[108:109], v[108:109], v[114:115]
	v_cvt_f32_ubyte1_e32 v117, v112
	v_cvt_f32_ubyte0_e32 v116, v112
	v_pk_mul_f32 v[126:127], v[102:103], v[108:109]
	v_cvt_f32_ubyte1_e32 v103, v113
	v_cvt_f32_ubyte0_e32 v102, v113
	v_pk_mul_f32 v[104:105], v[104:105], v[116:117]
	v_pk_mul_f32 v[102:103], v[106:107], v[102:103]
	v_pk_mul_f32 v[124:125], v[100:101], v[104:105]
	v_cvt_f32_ubyte3_e32 v101, v113
	v_cvt_f32_ubyte2_e32 v100, v113
	v_pk_mul_f32 v[120:121], v[88:89], v[102:103]
	v_pk_mul_f32 v[100:101], v[110:111], v[100:101]
	s_waitcnt vmcnt(0) lgkmcnt(0)
	v_cvt_f32_ubyte1_e32 v107, v144
	v_cvt_f32_ubyte0_e32 v88, v146
	v_cvt_f32_ubyte1_e32 v89, v146
	v_rcp_iflag_f32_e32 v88, v88
	v_rcp_iflag_f32_e32 v89, v89
	v_pk_mul_f32 v[122:123], v[90:91], v[100:101]
	v_cvt_f32_ubyte0_e32 v90, v147
	v_cvt_f32_ubyte1_e32 v91, v147
	v_rcp_iflag_f32_e32 v90, v90
	v_rcp_iflag_f32_e32 v91, v91
	v_cvt_f32_ubyte2_e32 v102, v147
	v_cvt_f32_ubyte3_e32 v103, v147
	v_cvt_f32_ubyte0_e32 v106, v144
	v_rcp_iflag_f32_e32 v102, v102
	v_rcp_iflag_f32_e32 v103, v103
	v_pk_mul_f32 v[88:89], v[88:89], v[106:107]
	v_cvt_f32_ubyte2_e32 v100, v146
	v_pk_mul_f32 v[148:149], v[96:97], v[88:89]
	v_cvt_f32_ubyte1_e32 v97, v145
	v_cvt_f32_ubyte0_e32 v96, v145
	v_pk_mul_f32 v[90:91], v[90:91], v[96:97]
	v_cvt_f32_ubyte3_e32 v101, v146
	v_cvt_f32_ubyte3_e32 v105, v144
	v_cvt_f32_ubyte2_e32 v104, v144
	v_cvt_f32_ubyte3_e32 v89, v145
	v_cvt_f32_ubyte2_e32 v88, v145
	v_pk_mul_f32 v[144:145], v[92:93], v[90:91]
	v_cvt_f32_ubyte2_e32 v92, v214
	v_cvt_f32_ubyte3_e32 v93, v214
	v_rcp_iflag_f32_e32 v100, v100
	v_rcp_iflag_f32_e32 v101, v101
	v_pk_mul_f32 v[88:89], v[102:103], v[88:89]
	v_rcp_iflag_f32_e32 v92, v92
	v_rcp_iflag_f32_e32 v93, v93
	v_pk_mul_f32 v[146:147], v[94:95], v[88:89]
	v_cvt_f32_ubyte0_e32 v88, v214
	v_cvt_f32_ubyte1_e32 v89, v214
	v_cvt_f32_ubyte0_e32 v90, v215
	v_cvt_f32_ubyte1_e32 v91, v215
	v_rcp_iflag_f32_e32 v88, v88
	v_rcp_iflag_f32_e32 v90, v90
	v_rcp_iflag_f32_e32 v89, v89
	v_rcp_iflag_f32_e32 v91, v91
	v_cvt_f32_ubyte2_e32 v94, v215
	v_cvt_f32_ubyte3_e32 v95, v215
	v_cvt_f32_ubyte3_e32 v97, v184
	v_cvt_f32_ubyte2_e32 v96, v184
	v_pk_mul_f32 v[100:101], v[100:101], v[104:105]
	v_rcp_iflag_f32_e32 v94, v94
	v_rcp_iflag_f32_e32 v95, v95
	v_pk_mul_f32 v[92:93], v[92:93], v[96:97]
	v_pk_mul_f32 v[150:151], v[98:99], v[100:101]
	v_cvt_f32_ubyte1_e32 v99, v184
	v_cvt_f32_ubyte0_e32 v98, v184
	v_pk_mul_f32 v[118:119], v[86:87], v[92:93]
	v_cvt_f32_ubyte1_e32 v87, v185
	v_cvt_f32_ubyte0_e32 v86, v185
	v_pk_mul_f32 v[88:89], v[88:89], v[98:99]
	v_pk_mul_f32 v[86:87], v[90:91], v[86:87]
	v_pk_mul_f32 v[116:117], v[84:85], v[88:89]
	v_cvt_f32_ubyte3_e32 v85, v185
	v_cvt_f32_ubyte2_e32 v84, v185
	v_pk_mul_f32 v[112:113], v[80:81], v[86:87]
	v_lshl_add_u64 v[80:81], v[182:183], 0, s[26:27]
	v_pk_mul_f32 v[84:85], v[94:95], v[84:85]
	s_nop 0
	v_pk_mul_f32 v[114:115], v[82:83], v[84:85]
	flat_load_dwordx2 v[84:85], v[80:81]
	flat_load_dwordx2 v[86:87], v[80:81] offset:2048
	flat_load_dwordx2 v[82:83], v[80:81] offset:128
	flat_load_dwordx2 v[88:89], v[80:81] offset:2176
	v_add_co_u32_e32 v90, vcc, s21, v80
	s_waitcnt vmcnt(0) lgkmcnt(0)
;     DI void mid(AccT& acc, const Unit& u, int seg, int wr, int wc, int fr, int fq) const {
;     ...
; #pragma unroll
;         for (int ai = 0; ai < 2; ++ai) {
; #pragma unroll
;             for (int mh = 0; mh < 2; ++mh) {
;                 u32x2 ra[2][2], rb[2][2];
; #pragma unroll
;                 for (int mm = 0; mm < 2; ++mm)
; #pragma unroll
;                     for (int bj = 0; bj < 2; ++bj) { const unsigned char* p = pa + (size_t)(mm * 16) * NGATE + bj * HALF; ra[mm][bj] = *(const u32x2*)p; rb[mm][bj] = *(const u32x2*)(p + 2048); }
; #pragma unroll
;                 for (int mm = 0; mm < 2; ++mm)
; #pragma unroll
;                     for (int bj = 0; bj < 2; ++bj) {
;                         float ga[8], gb[8];
;                         unpack_gate8(ra[mm][bj], ga); unpack_gate8(rb[mm][bj], gb);
;                         const int m = 2 * mh + mm;
; #pragma unroll
;                         for (int j = 0; j < 4; ++j) { const float r0 = ga[j] * __builtin_amdgcn_rcpf(gb[j]), r1 = ga[4 + j] * __builtin_amdgcn_rcpf(gb[4 + j]);
;                             acc[ai][bj][m][0][j] *= r0; acc[ai][bj][m][1][j] *= r1; } }
;                 pa += (size_t)(mh == 1 ? 96 : 32) * NGATE;
;                 asm volatile("" : "+v"(pa));
	v_cvt_f32_ubyte1_e32 v105, v84
	v_addc_co_u32_e32 v91, vcc, 0, v81, vcc
	flat_load_dwordx2 v[92:93], v[90:91]
	flat_load_dwordx2 v[94:95], v[90:91] offset:2048
	flat_load_dwordx2 v[182:183], v[90:91] offset:128
	s_nop 0
	flat_load_dwordx2 v[90:91], v[90:91] offset:2176
	v_cvt_f32_ubyte0_e32 v96, v86
	v_cvt_f32_ubyte1_e32 v97, v86
	v_cvt_f32_ubyte2_e32 v98, v86
	v_cvt_f32_ubyte3_e32 v99, v86
	v_cvt_f32_ubyte0_e32 v100, v87
	v_cvt_f32_ubyte1_e32 v101, v87
	v_cvt_f32_ubyte2_e32 v102, v87
	v_cvt_f32_ubyte3_e32 v103, v87
	v_rcp_iflag_f32_e32 v86, v96
	v_rcp_iflag_f32_e32 v87, v97
	v_rcp_iflag_f32_e32 v96, v100
	v_rcp_iflag_f32_e32 v97, v101
	v_rcp_iflag_f32_e32 v98, v98
	v_rcp_iflag_f32_e32 v100, v102
	v_rcp_iflag_f32_e32 v99, v99
	v_rcp_iflag_f32_e32 v101, v103
	v_cvt_f32_ubyte0_e32 v104, v84
	v_pk_mul_f32 v[86:87], v[86:87], v[104:105]
	v_cvt_f32_ubyte3_e32 v103, v84
	v_cvt_f32_ubyte2_e32 v102, v84
	v_pk_mul_f32 v[108:109], v[76:77], v[86:87]
	v_cvt_f32_ubyte3_e32 v77, v85
	v_cvt_f32_ubyte2_e32 v76, v85
	v_pk_mul_f32 v[98:99], v[98:99], v[102:103]
	v_pk_mul_f32 v[76:77], v[100:101], v[76:77]
	v_pk_mul_f32 v[110:111], v[78:79], v[98:99]
	v_cvt_f32_ubyte1_e32 v79, v85
	v_cvt_f32_ubyte0_e32 v78, v85
	v_pk_mul_f32 v[106:107], v[74:75], v[76:77]
	v_cvt_f32_ubyte2_e32 v76, v88
	v_cvt_f32_ubyte3_e32 v77, v88
	v_pk_mul_f32 v[78:79], v[96:97], v[78:79]
	v_rcp_iflag_f32_e32 v76, v76
	v_rcp_iflag_f32_e32 v77, v77
	v_pk_mul_f32 v[104:105], v[72:73], v[78:79]
	v_cvt_f32_ubyte0_e32 v72, v88
	v_cvt_f32_ubyte1_e32 v73, v88
	v_cvt_f32_ubyte0_e32 v74, v89
	v_cvt_f32_ubyte1_e32 v75, v89
	v_cvt_f32_ubyte2_e32 v78, v89
	v_cvt_f32_ubyte3_e32 v79, v89
	v_rcp_iflag_f32_e32 v72, v72
	v_rcp_iflag_f32_e32 v74, v74
	v_rcp_iflag_f32_e32 v73, v73
	v_rcp_iflag_f32_e32 v75, v75
	v_rcp_iflag_f32_e32 v84, v78
	v_rcp_iflag_f32_e32 v85, v79
	v_cvt_f32_ubyte3_e32 v79, v82
	v_cvt_f32_ubyte2_e32 v78, v82
	v_pk_mul_f32 v[76:77], v[76:77], v[78:79]
	v_cvt_f32_ubyte1_e32 v87, v82
	v_cvt_f32_ubyte0_e32 v86, v82
	v_pk_mul_f32 v[78:79], v[70:71], v[76:77]
	v_cvt_f32_ubyte1_e32 v71, v83
	v_cvt_f32_ubyte0_e32 v70, v83
	v_pk_mul_f32 v[72:73], v[72:73], v[86:87]
	v_pk_mul_f32 v[70:71], v[74:75], v[70:71]
	v_pk_mul_f32 v[76:77], v[68:69], v[72:73]
	v_cvt_f32_ubyte3_e32 v69, v83
	v_cvt_f32_ubyte2_e32 v68, v83
	v_pk_mul_f32 v[72:73], v[56:57], v[70:71]
	v_pk_mul_f32 v[68:69], v[84:85], v[68:69]
	s_waitcnt vmcnt(0) lgkmcnt(0)
	v_cvt_f32_ubyte1_e32 v85, v92
	v_cvt_f32_ubyte0_e32 v56, v94
	v_cvt_f32_ubyte1_e32 v57, v94
	v_rcp_iflag_f32_e32 v56, v56
	v_rcp_iflag_f32_e32 v57, v57
	v_pk_mul_f32 v[74:75], v[58:59], v[68:69]
	v_cvt_f32_ubyte0_e32 v58, v95
	v_cvt_f32_ubyte1_e32 v59, v95
	v_cvt_f32_ubyte2_e32 v70, v95
	v_cvt_f32_ubyte3_e32 v71, v95
	v_rcp_iflag_f32_e32 v58, v58
	v_rcp_iflag_f32_e32 v59, v59
	v_rcp_iflag_f32_e32 v70, v70
	v_rcp_iflag_f32_e32 v71, v71
	v_cvt_f32_ubyte0_e32 v84, v92
	v_pk_mul_f32 v[56:57], v[56:57], v[84:85]
	v_cvt_f32_ubyte2_e32 v68, v94
	v_cvt_f32_ubyte3_e32 v69, v94
	v_pk_mul_f32 v[100:101], v[64:65], v[56:57]
	v_cvt_f32_ubyte3_e32 v57, v93
	v_cvt_f32_ubyte2_e32 v56, v93
	v_cvt_f32_ubyte1_e32 v65, v93
	v_cvt_f32_ubyte0_e32 v64, v93
	v_rcp_iflag_f32_e32 v68, v68
	v_rcp_iflag_f32_e32 v69, v69
	v_pk_mul_f32 v[58:59], v[58:59], v[64:65]
	v_pk_mul_f32 v[56:57], v[70:71], v[56:57]
	v_pk_mul_f32 v[96:97], v[60:61], v[58:59]
	v_pk_mul_f32 v[98:99], v[62:63], v[56:57]
	v_cvt_f32_ubyte0_e32 v56, v90
	v_cvt_f32_ubyte1_e32 v57, v90
	v_cvt_f32_ubyte2_e32 v60, v90
	v_cvt_f32_ubyte3_e32 v61, v90
	v_rcp_iflag_f32_e32 v56, v56
	v_rcp_iflag_f32_e32 v57, v57
	v_rcp_iflag_f32_e32 v60, v60
	v_rcp_iflag_f32_e32 v61, v61
	v_cvt_f32_ubyte3_e32 v83, v92
	v_cvt_f32_ubyte2_e32 v82, v92
	v_cvt_f32_ubyte0_e32 v58, v91
	v_cvt_f32_ubyte1_e32 v59, v91
	v_cvt_f32_ubyte2_e32 v62, v91
	v_cvt_f32_ubyte3_e32 v63, v91
	v_pk_mul_f32 v[68:69], v[68:69], v[82:83]
	v_rcp_iflag_f32_e32 v58, v58
	v_rcp_iflag_f32_e32 v59, v59
	v_rcp_iflag_f32_e32 v62, v62
	v_rcp_iflag_f32_e32 v63, v63
	v_pk_mul_f32 v[102:103], v[66:67], v[68:69]
	v_cvt_f32_ubyte3_e32 v65, v182
	v_cvt_f32_ubyte2_e32 v64, v182
	v_cvt_f32_ubyte1_e32 v67, v182
	v_cvt_f32_ubyte0_e32 v66, v182
	v_pk_mul_f32 v[56:57], v[56:57], v[66:67]
	v_pk_mul_f32 v[60:61], v[60:61], v[64:65]
	v_pk_mul_f32 v[68:69], v[52:53], v[56:57]
	v_pk_mul_f32 v[70:71], v[54:55], v[60:61]
	v_cvt_f32_ubyte3_e32 v53, v183
	v_cvt_f32_ubyte2_e32 v52, v183
	v_cvt_f32_ubyte1_e32 v55, v183
	v_cvt_f32_ubyte0_e32 v54, v183
	v_lshl_add_u64 v[182:183], v[80:81], 0, s[24:25]
	v_pk_mul_f32 v[54:55], v[58:59], v[54:55]
	v_pk_mul_f32 v[52:53], v[62:63], v[52:53]
	v_pk_mul_f32 v[64:65], v[48:49], v[54:55]
	v_pk_mul_f32 v[66:67], v[50:51], v[52:53]
	flat_load_dwordx2 v[50:51], v[182:183]
	flat_load_dwordx2 v[52:53], v[182:183] offset:2048
	flat_load_dwordx2 v[48:49], v[182:183] offset:128
	flat_load_dwordx2 v[54:55], v[182:183] offset:2176
	v_add_co_u32_e32 v56, vcc, s21, v182
	s_waitcnt vmcnt(0) lgkmcnt(0)
;     DI void mid(AccT& acc, const Unit& u, int seg, int wr, int wc, int fr, int fq) const {
;     ...
; #pragma unroll
;         for (int ai = 0; ai < 2; ++ai) {
; #pragma unroll
;             for (int mh = 0; mh < 2; ++mh) {
;                 u32x2 ra[2][2], rb[2][2];
; #pragma unroll
;                 for (int mm = 0; mm < 2; ++mm)
; #pragma unroll
;                     for (int bj = 0; bj < 2; ++bj) { const unsigned char* p = pa + (size_t)(mm * 16) * NGATE + bj * HALF; ra[mm][bj] = *(const u32x2*)p; rb[mm][bj] = *(const u32x2*)(p + 2048); }
; #pragma unroll
;                 for (int mm = 0; mm < 2; ++mm)
; #pragma unroll
;                     for (int bj = 0; bj < 2; ++bj) {
;                         float ga[8], gb[8];
;                         unpack_gate8(ra[mm][bj], ga); unpack_gate8(rb[mm][bj], gb);
;                         const int m = 2 * mh + mm;
; #pragma unroll
;                         for (int j = 0; j < 4; ++j) { const float r0 = ga[j] * __builtin_amdgcn_rcpf(gb[j]), r1 = ga[4 + j] * __builtin_amdgcn_rcpf(gb[4 + j]);
;                             acc[ai][bj][m][0][j] *= r0; acc[ai][bj][m][1][j] *= r1; } }
;                 pa += (size_t)(mh == 1 ? 96 : 32) * NGATE;
;                 asm volatile("" : "+v"(pa));
	v_cvt_f32_ubyte1_e32 v85, v50
	v_addc_co_u32_e32 v57, vcc, 0, v183, vcc
	flat_load_dwordx2 v[80:81], v[56:57]
	flat_load_dwordx2 v[82:83], v[56:57] offset:2048
	flat_load_dwordx2 v[184:185], v[56:57] offset:128
	flat_load_dwordx2 v[214:215], v[56:57] offset:2176
	v_cvt_f32_ubyte0_e32 v56, v52
	v_cvt_f32_ubyte1_e32 v57, v52
	v_cvt_f32_ubyte2_e32 v58, v52
	v_cvt_f32_ubyte3_e32 v59, v52
	v_cvt_f32_ubyte0_e32 v60, v53
	v_cvt_f32_ubyte1_e32 v61, v53
	v_cvt_f32_ubyte2_e32 v62, v53
	v_cvt_f32_ubyte3_e32 v63, v53
	v_rcp_iflag_f32_e32 v52, v56
	v_rcp_iflag_f32_e32 v53, v57
	v_rcp_iflag_f32_e32 v58, v58
	v_rcp_iflag_f32_e32 v59, v59
	v_rcp_iflag_f32_e32 v56, v60
	v_rcp_iflag_f32_e32 v57, v61
	v_rcp_iflag_f32_e32 v60, v62
	v_rcp_iflag_f32_e32 v61, v63
	v_cvt_f32_ubyte3_e32 v63, v50
	v_cvt_f32_ubyte2_e32 v62, v50
	v_cvt_f32_ubyte0_e32 v84, v50
	v_pk_mul_f32 v[52:53], v[52:53], v[84:85]
	v_pk_mul_f32 v[58:59], v[58:59], v[62:63]
	v_pk_mul_f32 v[92:93], v[28:29], v[52:53]
	v_pk_mul_f32 v[94:95], v[30:31], v[58:59]
	v_cvt_f32_ubyte3_e32 v29, v51
	v_cvt_f32_ubyte2_e32 v28, v51
	v_cvt_f32_ubyte1_e32 v31, v51
	v_cvt_f32_ubyte0_e32 v30, v51
	v_pk_mul_f32 v[30:31], v[56:57], v[30:31]
	v_pk_mul_f32 v[28:29], v[60:61], v[28:29]
	v_pk_mul_f32 v[88:89], v[24:25], v[30:31]
	v_pk_mul_f32 v[90:91], v[26:27], v[28:29]
	v_cvt_f32_ubyte0_e32 v24, v54
	v_cvt_f32_ubyte1_e32 v25, v54
	v_cvt_f32_ubyte2_e32 v28, v54
	v_cvt_f32_ubyte3_e32 v29, v54
	v_rcp_iflag_f32_e32 v24, v24
	v_rcp_iflag_f32_e32 v25, v25
	v_rcp_iflag_f32_e32 v28, v28
	v_rcp_iflag_f32_e32 v29, v29
	v_cvt_f32_ubyte0_e32 v26, v55
	v_cvt_f32_ubyte1_e32 v27, v55
	v_cvt_f32_ubyte2_e32 v30, v55
	v_cvt_f32_ubyte3_e32 v31, v55
	v_rcp_iflag_f32_e32 v26, v26
	v_rcp_iflag_f32_e32 v27, v27
	v_rcp_iflag_f32_e32 v30, v30
	v_rcp_iflag_f32_e32 v31, v31
	v_cvt_f32_ubyte3_e32 v51, v48
	v_cvt_f32_ubyte2_e32 v50, v48
	v_cvt_f32_ubyte1_e32 v53, v48
	v_cvt_f32_ubyte0_e32 v52, v48
	v_pk_mul_f32 v[24:25], v[24:25], v[52:53]
	v_pk_mul_f32 v[28:29], v[28:29], v[50:51]
	v_pk_mul_f32 v[60:61], v[20:21], v[24:25]
	v_pk_mul_f32 v[62:63], v[22:23], v[28:29]
	v_cvt_f32_ubyte3_e32 v21, v49
	v_cvt_f32_ubyte2_e32 v20, v49
	v_cvt_f32_ubyte1_e32 v23, v49
	v_cvt_f32_ubyte0_e32 v22, v49
	v_pk_mul_f32 v[22:23], v[26:27], v[22:23]
	v_pk_mul_f32 v[20:21], v[30:31], v[20:21]
	v_pk_mul_f32 v[56:57], v[16:17], v[22:23]
	v_pk_mul_f32 v[58:59], v[18:19], v[20:21]
	s_waitcnt vmcnt(0) lgkmcnt(0)
	v_cvt_f32_ubyte3_e32 v25, v80
	v_cvt_f32_ubyte0_e32 v16, v82
	v_cvt_f32_ubyte1_e32 v17, v82
	v_cvt_f32_ubyte2_e32 v20, v82
	v_cvt_f32_ubyte3_e32 v21, v82
	v_rcp_iflag_f32_e32 v16, v16
	v_rcp_iflag_f32_e32 v17, v17
	v_rcp_iflag_f32_e32 v20, v20
	v_rcp_iflag_f32_e32 v21, v21
	v_cvt_f32_ubyte0_e32 v18, v83
	v_cvt_f32_ubyte1_e32 v19, v83
	v_cvt_f32_ubyte2_e32 v22, v83
	v_cvt_f32_ubyte3_e32 v23, v83
	v_rcp_iflag_f32_e32 v18, v18
	v_rcp_iflag_f32_e32 v19, v19
	v_rcp_iflag_f32_e32 v22, v22
	v_rcp_iflag_f32_e32 v23, v23
	v_cvt_f32_ubyte2_e32 v24, v80
	v_cvt_f32_ubyte1_e32 v27, v80
	v_cvt_f32_ubyte0_e32 v26, v80
	v_pk_mul_f32 v[16:17], v[16:17], v[26:27]
	v_pk_mul_f32 v[20:21], v[20:21], v[24:25]
	v_pk_mul_f32 v[84:85], v[12:13], v[16:17]
	v_pk_mul_f32 v[86:87], v[14:15], v[20:21]
	v_cvt_f32_ubyte3_e32 v13, v81
	v_cvt_f32_ubyte2_e32 v12, v81
	v_cvt_f32_ubyte1_e32 v15, v81
	v_cvt_f32_ubyte0_e32 v14, v81
	v_pk_mul_f32 v[14:15], v[18:19], v[14:15]
	v_pk_mul_f32 v[12:13], v[22:23], v[12:13]
	v_pk_mul_f32 v[80:81], v[8:9], v[14:15]
	v_pk_mul_f32 v[82:83], v[10:11], v[12:13]
	v_cvt_f32_ubyte0_e32 v8, v214
	v_cvt_f32_ubyte1_e32 v9, v214
	v_cvt_f32_ubyte2_e32 v12, v214
	v_cvt_f32_ubyte3_e32 v13, v214
	v_rcp_iflag_f32_e32 v8, v8
	v_rcp_iflag_f32_e32 v9, v9
	v_rcp_iflag_f32_e32 v12, v12
	v_rcp_iflag_f32_e32 v13, v13
	v_cvt_f32_ubyte0_e32 v10, v215
	v_cvt_f32_ubyte1_e32 v11, v215
	v_cvt_f32_ubyte2_e32 v14, v215
	v_cvt_f32_ubyte3_e32 v15, v215
	v_rcp_iflag_f32_e32 v10, v10
	v_rcp_iflag_f32_e32 v11, v11
	v_rcp_iflag_f32_e32 v14, v14
	v_rcp_iflag_f32_e32 v15, v15
	v_cvt_f32_ubyte3_e32 v17, v184
	v_cvt_f32_ubyte2_e32 v16, v184
	v_cvt_f32_ubyte1_e32 v19, v184
	v_cvt_f32_ubyte0_e32 v18, v184
	v_pk_mul_f32 v[8:9], v[8:9], v[18:19]
	v_pk_mul_f32 v[12:13], v[12:13], v[16:17]
	v_pk_mul_f32 v[52:53], v[4:5], v[8:9]
	v_pk_mul_f32 v[54:55], v[6:7], v[12:13]
	v_cvt_f32_ubyte3_e32 v5, v185
	v_cvt_f32_ubyte2_e32 v4, v185
	v_cvt_f32_ubyte1_e32 v7, v185
	v_cvt_f32_ubyte0_e32 v6, v185
	v_pk_mul_f32 v[6:7], v[10:11], v[6:7]
	v_pk_mul_f32 v[4:5], v[14:15], v[4:5]
	v_pk_mul_f32 v[48:49], v[0:1], v[6:7]
	v_pk_mul_f32 v[50:51], v[2:3], v[4:5]
	v_lshl_add_u64 v[0:1], v[182:183], 0, s[26:27]
